# per-tile accumulator zeroing with 64 v_mov_b64 instead of 128 v_mov_b32 (on the critical path before every tile's K-loop)
# speedup vs baseline: 1.0142x; 1.0074x over previous
.LBB0_130:
	s_add_u32 s38, s38, 0x80
	s_addc_u32 s39, s39, 0
	s_add_u32 s56, s88, 0x100
	s_addc_u32 s57, s89, 0
	s_mov_b32 s44, 0
	v_mov_b64_e32 v[2:3], 0
	v_mov_b64_e32 v[4:5], 0
	v_mov_b64_e32 v[6:7], 0
	v_mov_b64_e32 v[8:9], 0
	v_mov_b64_e32 v[10:11], 0
	v_mov_b64_e32 v[12:13], 0
	v_mov_b64_e32 v[14:15], 0
	v_mov_b64_e32 v[16:17], 0
	v_mov_b64_e32 v[18:19], 0
	v_mov_b64_e32 v[20:21], 0
	v_mov_b64_e32 v[22:23], 0
	v_mov_b64_e32 v[24:25], 0
	v_mov_b64_e32 v[26:27], 0
	v_mov_b64_e32 v[28:29], 0
	v_mov_b64_e32 v[30:31], 0
	v_mov_b64_e32 v[32:33], 0
	v_mov_b64_e32 v[34:35], 0
	v_mov_b64_e32 v[36:37], 0
	v_mov_b64_e32 v[38:39], 0
	v_mov_b64_e32 v[40:41], 0
	v_mov_b64_e32 v[42:43], 0
	v_mov_b64_e32 v[44:45], 0
	v_mov_b64_e32 v[46:47], 0
	v_mov_b64_e32 v[48:49], 0
	v_mov_b64_e32 v[50:51], 0
	v_mov_b64_e32 v[52:53], 0
	v_mov_b64_e32 v[54:55], 0
	v_mov_b64_e32 v[56:57], 0
	v_mov_b64_e32 v[58:59], 0
	v_mov_b64_e32 v[60:61], 0
	v_mov_b64_e32 v[62:63], 0
	v_mov_b64_e32 v[64:65], 0
	v_mov_b64_e32 v[66:67], 0
	v_mov_b64_e32 v[68:69], 0
	v_mov_b64_e32 v[70:71], 0
	v_mov_b64_e32 v[72:73], 0
	v_mov_b64_e32 v[74:75], 0
	v_mov_b64_e32 v[76:77], 0
	v_mov_b64_e32 v[78:79], 0
	v_mov_b64_e32 v[80:81], 0
	v_mov_b64_e32 v[82:83], 0
	v_mov_b64_e32 v[84:85], 0
	v_mov_b64_e32 v[86:87], 0
	v_mov_b64_e32 v[88:89], 0
	v_mov_b64_e32 v[90:91], 0
	v_mov_b64_e32 v[92:93], 0
	v_mov_b64_e32 v[94:95], 0
	v_mov_b64_e32 v[96:97], 0
	v_mov_b64_e32 v[98:99], 0
	v_mov_b64_e32 v[100:101], 0
	v_mov_b64_e32 v[102:103], 0
	v_mov_b64_e32 v[104:105], 0
	v_mov_b64_e32 v[106:107], 0
	v_mov_b64_e32 v[108:109], 0
	v_mov_b64_e32 v[110:111], 0
	v_mov_b64_e32 v[112:113], 0
	v_mov_b64_e32 v[114:115], 0
	v_mov_b64_e32 v[116:117], 0
	v_mov_b64_e32 v[118:119], 0
	v_mov_b64_e32 v[120:121], 0
	v_mov_b64_e32 v[122:123], 0
	v_mov_b64_e32 v[124:125], 0
	v_mov_b64_e32 v[126:127], 0
	v_mov_b64_e32 v[128:129], 0
